# scan: o tile packed in place and stored by waves 0-3 in the next step just before its first barrier (idle slot, empty memory pipe); last tile flushed after the loop
# speedup vs baseline: 1.0458x; 1.0033x over previous
.LBB0_1143:
	s_cmp_lg_u64 s[8:9], 0
	s_cbranch_scc0 .Lscan_nofl
	global_store_dwordx4 v[96:97], v[80:83], off
	global_store_dwordx4 v[96:97], v[84:87], off offset:32
	global_store_dwordx4 v[98:99], v[88:91], off
	global_store_dwordx4 v[98:99], v[92:95], off offset:32

.LBB0_1152:
	s_or_b64 exec, exec, s[44:45]
	s_add_i32 s90, s81, 1
	s_cmp_lt_u32 s81, 5
	s_cbranch_scc1 .Lscan_nost
	s_cmp_lg_u64 s[8:9], 0
	s_cbranch_scc0 .Lscan_nost
	global_store_dwordx4 v[96:97], v[80:83], off
	global_store_dwordx4 v[96:97], v[84:87], off offset:32
	global_store_dwordx4 v[98:99], v[88:91], off
	global_store_dwordx4 v[98:99], v[92:95], off offset:32
.Lscan_nost:
	s_cmp_eq_u32 s89, -1
	s_waitcnt lgkmcnt(0)
	s_barrier
	s_cbranch_scc1 .LBB0_1162
	s_cmp_lg_u64 s[8:9], 0
	s_cbranch_scc0 .LBB0_1162

.Lscan_b2:
	s_waitcnt lgkmcnt(0)
	s_barrier
	s_and_saveexec_b64 s[44:45], s[8:9]
	s_cbranch_execz .LBB0_1171
	v_add_u32_e32 v0, v180, v192
	ds_read_b128 v[2:5], v0 offset:49152
	v_add_u32_e32 v0, v182, v192
	ds_read_b128 v[12:15], v0
	ds_read_b128 v[112:115], v0 offset:4096
	v_add_u32_e32 v0, v180, v193
	ds_read_b128 v[116:119], v0 offset:49152
	v_add_u32_e32 v0, v182, v193
	ds_read_b128 v[120:123], v0
	ds_read_b128 v[124:127], v0 offset:4096
	s_ashr_i32 s81, s80, 31
	s_lshl_b64 s[60:61], s[80:81], 11
	s_waitcnt lgkmcnt(4)
	v_mfma_f32_32x32x16_bf16 v[80:95], v[2:5], v[12:15], v[80:95]
	s_waitcnt lgkmcnt(3)
	v_mfma_f32_32x32x16_bf16 v[96:111], v[2:5], v[112:115], v[96:111]
	v_add_u32_e32 v0, v180, v195
	ds_read_b128 v[2:5], v0 offset:49152
	v_add_u32_e32 v0, v182, v195
	ds_read_b128 v[12:15], v0
	ds_read_b128 v[112:115], v0 offset:4096
	s_waitcnt lgkmcnt(4)
	v_mfma_f32_32x32x16_bf16 v[80:95], v[116:119], v[120:123], v[80:95]
	s_waitcnt lgkmcnt(3)
	v_mfma_f32_32x32x16_bf16 v[96:111], v[116:119], v[124:127], v[96:111]
	v_add_u32_e32 v0, v180, v196
	ds_read_b128 v[116:119], v0 offset:49152
	v_add_u32_e32 v0, v182, v196
	ds_read_b128 v[120:123], v0
	ds_read_b128 v[124:127], v0 offset:4096
	s_waitcnt lgkmcnt(4)
	v_mfma_f32_32x32x16_bf16 v[80:95], v[2:5], v[12:15], v[80:95]
	s_waitcnt lgkmcnt(3)
	v_mfma_f32_32x32x16_bf16 v[96:111], v[2:5], v[112:115], v[96:111]
	s_waitcnt lgkmcnt(1)
	v_mfma_f32_32x32x16_bf16 v[80:95], v[116:119], v[120:123], v[80:95]
	s_waitcnt lgkmcnt(0)
	v_mfma_f32_32x32x16_bf16 v[96:111], v[116:119], v[124:127], v[96:111]
	v_mbcnt_lo_u32_b32 v0, -1, 0
	v_mbcnt_hi_u32_b32 v0, -1, v0
	v_and_b32_e32 v120, 31, v0
	v_lshrrev_b32_e32 v121, 5, v0
	v_mul_u32_u24_e32 v120, 0x7fe, v120
	v_mul_u32_u24_e32 v121, 0x1ff0, v121
	v_sub_u32_e32 v120, v120, v121
	v_ashrrev_i32_e32 v121, 31, v120
	v_lshl_add_u64 v[124:125], v[168:169], 0, v[120:121]
	v_lshl_add_u64 v[124:125], v[124:125], 0, s[60:61]
	s_mov_b64 s[60:61], 0x10000
	v_lshl_add_u64 v[126:127], v[124:125], 0, s[60:61]
	s_nop 3
	v_cvt_pk_bf16_f32 v80, v80, v81
	v_cvt_pk_bf16_f32 v81, v82, v83
	v_cvt_pk_bf16_f32 v82, v84, v85
	v_cvt_pk_bf16_f32 v83, v86, v87
	s_nop 1
	v_permlane32_swap_b32_e32 v80, v82
	v_permlane32_swap_b32_e32 v81, v83
	v_cvt_pk_bf16_f32 v84, v88, v89
	v_cvt_pk_bf16_f32 v85, v90, v91
	v_cvt_pk_bf16_f32 v86, v92, v93
	v_cvt_pk_bf16_f32 v87, v94, v95
	s_nop 1
	v_permlane32_swap_b32_e32 v84, v86
	v_permlane32_swap_b32_e32 v85, v87
	v_cvt_pk_bf16_f32 v88, v96, v97
	v_cvt_pk_bf16_f32 v89, v98, v99
	v_cvt_pk_bf16_f32 v90, v100, v101
	v_cvt_pk_bf16_f32 v91, v102, v103
	s_nop 1
	v_permlane32_swap_b32_e32 v88, v90
	v_permlane32_swap_b32_e32 v89, v91
	v_cvt_pk_bf16_f32 v92, v104, v105
	v_cvt_pk_bf16_f32 v93, v106, v107
	v_cvt_pk_bf16_f32 v94, v108, v109
	v_cvt_pk_bf16_f32 v95, v110, v111
	s_nop 1
	v_permlane32_swap_b32_e32 v92, v94
	v_permlane32_swap_b32_e32 v93, v95
	v_mov_b64_e32 v[96:97], v[124:125]
	v_mov_b64_e32 v[98:99], v[126:127]
